# P5 residual LDS-DMA prefetch in K loop + epilogue x loads without the nt hint (so they can hit lines the prefetch brought in)
# speedup vs baseline: 1.0064x; 1.0064x over previous
; __device__ __forceinline__ unsigned cvt_pk_bf16(float lo, float hi) { unsigned r; asm volatile("v_cvt_pk_bf16_f32 %0, %1, %2" : "=v"(r) : "v"(lo), "v"(hi)); return r; }
;     __device__ __forceinline__ void operator()(const f32x4 (&acc)[2][2][4][2], const Unit& u, int wr, int wc, int fr, int fq) const {
;         const int row0 = u.pm * BM + wr * 64 + fr, col0 = u.pn * BM + wc * 32 + 4 * fq, b = (u.pm * BM) >> 12;
;         f32x4 gv[2][2], Gv[2][2];
; #pragma unroll
;         for (int bj = 0; bj < 2; ++bj)
; #pragma unroll
;             for (int n = 0; n < 2; ++n) { const int c = col0 + bj * HALF + n * 16; gv[bj][n] = *(const f32x4*)(mod + (size_t)b * 12288 + 2 * 2048 + c);
;                 Gv[bj][n] = *(const f32x4*)(g2 + c) * (*(const f32x4*)(mod + (size_t)b * 12288 + 4 * 2048 + c) + 1.0f); }
;         float* prow = part + (size_t)(u.pn * 4 + wc) * 16384;
; #pragma unroll
;         for (int ai = 0; ai < 2; ++ai)
; #pragma unroll
;             for (int m = 0; m < 4; ++m) { const int row = row0 + ai * HALF + m * 16; const size_t off = (size_t)row * 2048 + col0; float ss = 0.f;
; #pragma unroll
;                 for (int bj = 0; bj < 2; ++bj)
; #pragma unroll
;                     for (int n = 0; n < 2; ++n) { const f32x4 bs = __builtin_nontemporal_load((const f32x4*)(base + off + bj * HALF + n * 16)); const f32x4 x1 = bs + gv[bj][n] * acc[ai][bj][m][n];
;                         *(f32x4*)(out + off + bj * HALF + n * 16) = x1; ss += (x1.x * x1.x + x1.y * x1.y) + (x1.z * x1.z + x1.w * x1.w);
;                         const f32x4 hh = x1 * Gv[bj][n]; u32x2 w; w.x = cvt_pk_bf16(hh.x, hh.y); w.y = cvt_pk_bf16(hh.z, hh.w); *(u32x2*)(A2 + off + bj * HALF + n * 16) = w; }
.LBB0_897:
	v_readlane_b32 s98, v236, 7
	v_readlane_b32 s99, v236, 8
	v_readlane_b32 s76, v236, 35
	v_readlane_b32 s77, v236, 36
	s_ashr_i32 s25, s36, 4
	s_mul_hi_i32 s27, s25, 0xc000
	s_mul_i32 s25, s25, 0xc000
	s_add_u32 s38, s68, s25
	s_addc_u32 s39, s69, s27
	s_add_u32 s40, s38, 0x8000
	s_addc_u32 s41, s39, 0
	s_add_u32 s38, s38, 0x4000
	s_addc_u32 s39, s39, 0
	v_lshl_add_u32 v164, s36, 8, v166
	v_lshl_or_b32 v165, s34, 8, v168
	v_lshlrev_b32_e32 v173, 2, v165
	v_xor_b32_e32 v216, 16, v172
	v_xor_b32_e32 v217, 32, v172
	v_lshlrev_b32_e32 v216, 2, v216
	v_lshlrev_b32_e32 v217, 2, v217
	global_load_dwordx4 v[72:75], v173, s[38:39]
	global_load_dwordx4 v[84:87], v173, s[38:39] offset:64
	global_load_dwordx4 v[92:95], v173, s[38:39] offset:512
	global_load_dwordx4 v[96:99], v173, s[38:39] offset:576
	global_load_dwordx4 v[156:159], v173, s[40:41]
	global_load_dwordx4 v[160:163], v173, s[40:41] offset:64
	global_load_dwordx4 v[174:177], v173, s[40:41] offset:512
	global_load_dwordx4 v[178:181], v173, s[40:41] offset:576
	global_load_dwordx4 v[182:185], v173, s[76:77]
	global_load_dwordx4 v[188:191], v173, s[76:77] offset:64
	global_load_dwordx4 v[192:195], v173, s[76:77] offset:512
	global_load_dwordx4 v[196:199], v173, s[76:77] offset:576
	v_lshl_add_u32 v164, v164, 13, v173
	v_mov_b32_e32 v165, v164
	v_lshrrev_b32_e32 v173, 1, v164
	global_load_dwordx4 v[200:203], v164, s[98:99]
	global_load_dwordx4 v[204:207], v164, s[98:99] offset:64
	global_load_dwordx4 v[208:211], v164, s[98:99] offset:512
	global_load_dwordx4 v[212:215], v164, s[98:99] offset:576
	v_add_u32_e32 v164, 0x20000, v164
	s_waitcnt vmcnt(4)
	v_pk_add_f32 v[156:157], v[156:157], 1.0 op_sel_hi:[1,0]
	v_pk_add_f32 v[158:159], v[158:159], 1.0 op_sel_hi:[1,0]
	v_pk_mul_f32 v[182:183], v[182:183], v[156:157]
	v_pk_mul_f32 v[184:185], v[184:185], v[158:159]
	v_pk_add_f32 v[160:161], v[160:161], 1.0 op_sel_hi:[1,0]
	v_pk_add_f32 v[162:163], v[162:163], 1.0 op_sel_hi:[1,0]
	v_pk_mul_f32 v[188:189], v[188:189], v[160:161]
	v_pk_mul_f32 v[190:191], v[190:191], v[162:163]
	v_pk_add_f32 v[174:175], v[174:175], 1.0 op_sel_hi:[1,0]
	v_pk_add_f32 v[176:177], v[176:177], 1.0 op_sel_hi:[1,0]
	v_pk_mul_f32 v[192:193], v[192:193], v[174:175]
	v_pk_mul_f32 v[194:195], v[194:195], v[176:177]
	v_pk_add_f32 v[178:179], v[178:179], 1.0 op_sel_hi:[1,0]
	v_pk_add_f32 v[180:181], v[180:181], 1.0 op_sel_hi:[1,0]
	v_pk_mul_f32 v[196:197], v[196:197], v[178:179]
	v_pk_mul_f32 v[198:199], v[198:199], v[180:181]
	global_load_dwordx4 v[156:159], v164, s[98:99]
	global_load_dwordx4 v[160:163], v164, s[98:99] offset:64
	global_load_dwordx4 v[174:177], v164, s[98:99] offset:512
	global_load_dwordx4 v[178:181], v164, s[98:99] offset:576
	v_add_u32_e32 v164, 0x20000, v164
	s_waitcnt vmcnt(7)
	v_pk_fma_f32 v[200:201], v[140:141], v[72:73], v[200:201]
	v_pk_fma_f32 v[202:203], v[142:143], v[74:75], v[202:203]
	global_store_dwordx4 v165, v[200:203], s[66:67]
	v_pk_mul_f32 v[140:141], v[200:201], v[182:183]
	v_pk_mul_f32 v[142:143], v[202:203], v[184:185]
	v_cvt_pk_bf16_f32 v140, v140, v141
	v_cvt_pk_bf16_f32 v141, v142, v143
	global_store_dwordx2 v173, v[140:141], s[8:9]
	v_mul_f32_e32 v142, v200, v200
	v_fmac_f32_e32 v142, v201, v201
	v_fmac_f32_e32 v142, v202, v202
	v_fmac_f32_e32 v142, v203, v203
	global_load_dwordx4 v[200:203], v164, s[98:99]
	s_waitcnt vmcnt(9)
	v_pk_fma_f32 v[204:205], v[136:137], v[84:85], v[204:205]
	v_pk_fma_f32 v[206:207], v[138:139], v[86:87], v[206:207]
	global_store_dwordx4 v165, v[204:207], s[66:67] offset:64
	v_pk_mul_f32 v[136:137], v[204:205], v[188:189]
	v_pk_mul_f32 v[138:139], v[206:207], v[190:191]
	v_cvt_pk_bf16_f32 v136, v136, v137
	v_cvt_pk_bf16_f32 v137, v138, v139
	global_store_dwordx2 v173, v[136:137], s[8:9] offset:32
	v_fmac_f32_e32 v142, v204, v204
	v_fmac_f32_e32 v142, v205, v205
	v_fmac_f32_e32 v142, v206, v206
	v_fmac_f32_e32 v142, v207, v207
	global_load_dwordx4 v[204:207], v164, s[98:99] offset:64
	s_waitcnt vmcnt(11)
	v_pk_fma_f32 v[208:209], v[132:133], v[92:93], v[208:209]
	v_pk_fma_f32 v[210:211], v[134:135], v[94:95], v[210:211]
	global_store_dwordx4 v165, v[208:211], s[66:67] offset:512
	v_pk_mul_f32 v[132:133], v[208:209], v[192:193]
	v_pk_mul_f32 v[134:135], v[210:211], v[194:195]
	v_cvt_pk_bf16_f32 v132, v132, v133
	v_cvt_pk_bf16_f32 v133, v134, v135
	global_store_dwordx2 v173, v[132:133], s[8:9] offset:256
	v_fmac_f32_e32 v142, v208, v208
	v_fmac_f32_e32 v142, v209, v209
	v_fmac_f32_e32 v142, v210, v210
	v_fmac_f32_e32 v142, v211, v211
	global_load_dwordx4 v[208:211], v164, s[98:99] offset:512
	s_waitcnt vmcnt(13)
	v_pk_fma_f32 v[212:213], v[128:129], v[96:97], v[212:213]
	v_pk_fma_f32 v[214:215], v[130:131], v[98:99], v[214:215]
	global_store_dwordx4 v165, v[212:215], s[66:67] offset:576
	v_pk_mul_f32 v[128:129], v[212:213], v[196:197]
	v_pk_mul_f32 v[130:131], v[214:215], v[198:199]
	v_cvt_pk_bf16_f32 v128, v128, v129
	v_cvt_pk_bf16_f32 v129, v130, v131
	global_store_dwordx2 v173, v[128:129], s[8:9] offset:288
	v_fmac_f32_e32 v142, v212, v212
	v_fmac_f32_e32 v142, v213, v213
	v_fmac_f32_e32 v142, v214, v214
	v_fmac_f32_e32 v142, v215, v215
	v_add_u32_e32 v165, 0x20000, v165
	v_lshrrev_b32_e32 v173, 1, v165
	global_load_dwordx4 v[212:215], v164, s[98:99] offset:576
	v_add_u32_e32 v164, 0x20000, v164
	s_waitcnt vmcnt(15)
	v_pk_fma_f32 v[156:157], v[124:125], v[72:73], v[156:157]
	v_pk_fma_f32 v[158:159], v[126:127], v[74:75], v[158:159]
	global_store_dwordx4 v165, v[156:159], s[66:67]
	v_pk_mul_f32 v[124:125], v[156:157], v[182:183]
	v_pk_mul_f32 v[126:127], v[158:159], v[184:185]
	v_cvt_pk_bf16_f32 v124, v124, v125
	v_cvt_pk_bf16_f32 v125, v126, v127
	global_store_dwordx2 v173, v[124:125], s[8:9]
	v_mul_f32_e32 v126, v156, v156
	v_fmac_f32_e32 v126, v157, v157
	v_fmac_f32_e32 v126, v158, v158
	v_fmac_f32_e32 v126, v159, v159
	global_load_dwordx4 v[156:159], v164, s[98:99]
	s_waitcnt vmcnt(17)
; __device__ __forceinline__ unsigned cvt_pk_bf16(float lo, float hi) { unsigned r; asm volatile("v_cvt_pk_bf16_f32 %0, %1, %2" : "=v"(r) : "v"(lo), "v"(hi)); return r; }
;     __device__ __forceinline__ void operator()(const f32x4 (&acc)[2][2][4][2], const Unit& u, int wr, int wc, int fr, int fq) const {
;     ...
;         for (int ai = 0; ai < 2; ++ai)
; #pragma unroll
;             for (int m = 0; m < 4; ++m) { const int row = row0 + ai * HALF + m * 16; const size_t off = (size_t)row * 2048 + col0; float ss = 0.f;
; #pragma unroll
;                 for (int bj = 0; bj < 2; ++bj)
; #pragma unroll
;                     for (int n = 0; n < 2; ++n) { const f32x4 bs = __builtin_nontemporal_load((const f32x4*)(base + off + bj * HALF + n * 16)); const f32x4 x1 = bs + gv[bj][n] * acc[ai][bj][m][n];
;                         *(f32x4*)(out + off + bj * HALF + n * 16) = x1; ss += (x1.x * x1.x + x1.y * x1.y) + (x1.z * x1.z + x1.w * x1.w);
;                         const f32x4 hh = x1 * Gv[bj][n]; u32x2 w; w.x = cvt_pk_bf16(hh.x, hh.y); w.y = cvt_pk_bf16(hh.z, hh.w); *(u32x2*)(A2 + off + bj * HALF + n * 16) = w; }
	v_pk_fma_f32 v[160:161], v[120:121], v[84:85], v[160:161]
	v_pk_fma_f32 v[162:163], v[122:123], v[86:87], v[162:163]
	global_store_dwordx4 v165, v[160:163], s[66:67] offset:64
	v_pk_mul_f32 v[120:121], v[160:161], v[188:189]
	v_pk_mul_f32 v[122:123], v[162:163], v[190:191]
	v_cvt_pk_bf16_f32 v120, v120, v121
	v_cvt_pk_bf16_f32 v121, v122, v123
	global_store_dwordx2 v173, v[120:121], s[8:9] offset:32
	v_fmac_f32_e32 v126, v160, v160
	v_fmac_f32_e32 v126, v161, v161
	v_fmac_f32_e32 v126, v162, v162
	v_fmac_f32_e32 v126, v163, v163
	global_load_dwordx4 v[160:163], v164, s[98:99] offset:64
	s_waitcnt vmcnt(19)
	v_pk_fma_f32 v[174:175], v[116:117], v[92:93], v[174:175]
	v_pk_fma_f32 v[176:177], v[118:119], v[94:95], v[176:177]
	global_store_dwordx4 v165, v[174:177], s[66:67] offset:512
	v_pk_mul_f32 v[116:117], v[174:175], v[192:193]
	v_pk_mul_f32 v[118:119], v[176:177], v[194:195]
	v_cvt_pk_bf16_f32 v116, v116, v117
	v_cvt_pk_bf16_f32 v117, v118, v119
	global_store_dwordx2 v173, v[116:117], s[8:9] offset:256
	v_fmac_f32_e32 v126, v174, v174
	v_fmac_f32_e32 v126, v175, v175
	v_fmac_f32_e32 v126, v176, v176
	v_fmac_f32_e32 v126, v177, v177
	global_load_dwordx4 v[174:177], v164, s[98:99] offset:512
	s_waitcnt vmcnt(21)
	v_pk_fma_f32 v[178:179], v[112:113], v[96:97], v[178:179]
	v_pk_fma_f32 v[180:181], v[114:115], v[98:99], v[180:181]
	global_store_dwordx4 v165, v[178:181], s[66:67] offset:576
	v_pk_mul_f32 v[112:113], v[178:179], v[196:197]
	v_pk_mul_f32 v[114:115], v[180:181], v[198:199]
	v_cvt_pk_bf16_f32 v112, v112, v113
	v_cvt_pk_bf16_f32 v113, v114, v115
	global_store_dwordx2 v173, v[112:113], s[8:9] offset:288
	v_fmac_f32_e32 v126, v178, v178
	v_fmac_f32_e32 v126, v179, v179
	v_fmac_f32_e32 v126, v180, v180
	v_fmac_f32_e32 v126, v181, v181
	v_add_u32_e32 v165, 0x20000, v165
	v_lshrrev_b32_e32 v173, 1, v165
	global_load_dwordx4 v[178:181], v164, s[98:99] offset:576
	v_add_u32_e32 v164, 0xa0000, v164
	s_waitcnt vmcnt(21)
	v_pk_fma_f32 v[200:201], v[108:109], v[72:73], v[200:201]
	v_pk_fma_f32 v[202:203], v[110:111], v[74:75], v[202:203]
	global_store_dwordx4 v165, v[200:203], s[66:67]
	v_pk_mul_f32 v[108:109], v[200:201], v[182:183]
	v_pk_mul_f32 v[110:111], v[202:203], v[184:185]
	v_cvt_pk_bf16_f32 v108, v108, v109
	v_cvt_pk_bf16_f32 v109, v110, v111
	global_store_dwordx2 v173, v[108:109], s[8:9]
	v_mul_f32_e32 v110, v200, v200
	v_fmac_f32_e32 v110, v201, v201
	v_fmac_f32_e32 v110, v202, v202
	v_fmac_f32_e32 v110, v203, v203
	global_load_dwordx4 v[200:203], v164, s[98:99]
	s_waitcnt vmcnt(21)
	v_pk_fma_f32 v[204:205], v[104:105], v[84:85], v[204:205]
	v_pk_fma_f32 v[206:207], v[106:107], v[86:87], v[206:207]
	global_store_dwordx4 v165, v[204:207], s[66:67] offset:64
	v_pk_mul_f32 v[104:105], v[204:205], v[188:189]
	v_pk_mul_f32 v[106:107], v[206:207], v[190:191]
	v_cvt_pk_bf16_f32 v104, v104, v105
	v_cvt_pk_bf16_f32 v105, v106, v107
	global_store_dwordx2 v173, v[104:105], s[8:9] offset:32
	v_fmac_f32_e32 v110, v204, v204
	v_fmac_f32_e32 v110, v205, v205
	v_fmac_f32_e32 v110, v206, v206
	v_fmac_f32_e32 v110, v207, v207
	global_load_dwordx4 v[204:207], v164, s[98:99] offset:64
	s_waitcnt vmcnt(21)
	v_pk_fma_f32 v[208:209], v[100:101], v[92:93], v[208:209]
	v_pk_fma_f32 v[210:211], v[102:103], v[94:95], v[210:211]
	global_store_dwordx4 v165, v[208:211], s[66:67] offset:512
	v_pk_mul_f32 v[100:101], v[208:209], v[192:193]
	v_pk_mul_f32 v[102:103], v[210:211], v[194:195]
	v_cvt_pk_bf16_f32 v100, v100, v101
	v_cvt_pk_bf16_f32 v101, v102, v103
	global_store_dwordx2 v173, v[100:101], s[8:9] offset:256
	v_fmac_f32_e32 v110, v208, v208
	v_fmac_f32_e32 v110, v209, v209
	v_fmac_f32_e32 v110, v210, v210
	v_fmac_f32_e32 v110, v211, v211
	global_load_dwordx4 v[208:211], v164, s[98:99] offset:512
	s_waitcnt vmcnt(21)
	v_pk_fma_f32 v[212:213], v[88:89], v[96:97], v[212:213]
	v_pk_fma_f32 v[214:215], v[90:91], v[98:99], v[214:215]
	global_store_dwordx4 v165, v[212:215], s[66:67] offset:576
	v_pk_mul_f32 v[88:89], v[212:213], v[196:197]
	v_pk_mul_f32 v[90:91], v[214:215], v[198:199]
	v_cvt_pk_bf16_f32 v88, v88, v89
	v_cvt_pk_bf16_f32 v89, v90, v91
	global_store_dwordx2 v173, v[88:89], s[8:9] offset:288
	v_fmac_f32_e32 v110, v212, v212
	v_fmac_f32_e32 v110, v213, v213
	v_fmac_f32_e32 v110, v214, v214
	v_fmac_f32_e32 v110, v215, v215
	v_add_u32_e32 v165, 0x20000, v165
	v_lshrrev_b32_e32 v173, 1, v165
	global_load_dwordx4 v[212:215], v164, s[98:99] offset:576
	v_add_u32_e32 v164, 0x20000, v164
	s_waitcnt vmcnt(21)
	v_pk_fma_f32 v[156:157], v[80:81], v[72:73], v[156:157]
	v_pk_fma_f32 v[158:159], v[82:83], v[74:75], v[158:159]
	global_store_dwordx4 v165, v[156:159], s[66:67]
	v_pk_mul_f32 v[80:81], v[156:157], v[182:183]
	v_pk_mul_f32 v[82:83], v[158:159], v[184:185]
	v_cvt_pk_bf16_f32 v80, v80, v81
	v_cvt_pk_bf16_f32 v81, v82, v83
	global_store_dwordx2 v173, v[80:81], s[8:9]
	v_mul_f32_e32 v82, v156, v156
	v_fmac_f32_e32 v82, v157, v157
	v_fmac_f32_e32 v82, v158, v158
	v_fmac_f32_e32 v82, v159, v159
	global_load_dwordx4 v[156:159], v164, s[98:99]
	s_waitcnt vmcnt(21)
	v_pk_fma_f32 v[160:161], v[76:77], v[84:85], v[160:161]
	v_pk_fma_f32 v[162:163], v[78:79], v[86:87], v[162:163]
	global_store_dwordx4 v165, v[160:163], s[66:67] offset:64
	v_pk_mul_f32 v[76:77], v[160:161], v[188:189]
	v_pk_mul_f32 v[78:79], v[162:163], v[190:191]
	v_cvt_pk_bf16_f32 v76, v76, v77
	v_cvt_pk_bf16_f32 v77, v78, v79
	global_store_dwordx2 v173, v[76:77], s[8:9] offset:32
	v_fmac_f32_e32 v82, v160, v160
	v_fmac_f32_e32 v82, v161, v161
	v_fmac_f32_e32 v82, v162, v162
	v_fmac_f32_e32 v82, v163, v163
	global_load_dwordx4 v[160:163], v164, s[98:99] offset:64
	s_waitcnt vmcnt(21)
; __device__ __forceinline__ unsigned cvt_pk_bf16(float lo, float hi) { unsigned r; asm volatile("v_cvt_pk_bf16_f32 %0, %1, %2" : "=v"(r) : "v"(lo), "v"(hi)); return r; }
;     __device__ __forceinline__ void operator()(const f32x4 (&acc)[2][2][4][2], const Unit& u, int wr, int wc, int fr, int fq) const {
;     ...
;         for (int ai = 0; ai < 2; ++ai)
; #pragma unroll
;             for (int m = 0; m < 4; ++m) { const int row = row0 + ai * HALF + m * 16; const size_t off = (size_t)row * 2048 + col0; float ss = 0.f;
; #pragma unroll
;                 for (int bj = 0; bj < 2; ++bj)
; #pragma unroll
;                     for (int n = 0; n < 2; ++n) { const f32x4 bs = __builtin_nontemporal_load((const f32x4*)(base + off + bj * HALF + n * 16)); const f32x4 x1 = bs + gv[bj][n] * acc[ai][bj][m][n];
;                         *(f32x4*)(out + off + bj * HALF + n * 16) = x1; ss += (x1.x * x1.x + x1.y * x1.y) + (x1.z * x1.z + x1.w * x1.w);
;                         const f32x4 hh = x1 * Gv[bj][n]; u32x2 w; w.x = cvt_pk_bf16(hh.x, hh.y); w.y = cvt_pk_bf16(hh.z, hh.w); *(u32x2*)(A2 + off + bj * HALF + n * 16) = w; }
	v_pk_fma_f32 v[174:175], v[68:69], v[92:93], v[174:175]
	v_pk_fma_f32 v[176:177], v[70:71], v[94:95], v[176:177]
	global_store_dwordx4 v165, v[174:177], s[66:67] offset:512
	v_pk_mul_f32 v[68:69], v[174:175], v[192:193]
	v_pk_mul_f32 v[70:71], v[176:177], v[194:195]
	v_cvt_pk_bf16_f32 v68, v68, v69
	v_cvt_pk_bf16_f32 v69, v70, v71
	global_store_dwordx2 v173, v[68:69], s[8:9] offset:256
	v_fmac_f32_e32 v82, v174, v174
	v_fmac_f32_e32 v82, v175, v175
	v_fmac_f32_e32 v82, v176, v176
	v_fmac_f32_e32 v82, v177, v177
	global_load_dwordx4 v[174:177], v164, s[98:99] offset:512
	s_waitcnt vmcnt(21)
	v_pk_fma_f32 v[178:179], v[64:65], v[96:97], v[178:179]
	v_pk_fma_f32 v[180:181], v[66:67], v[98:99], v[180:181]
	global_store_dwordx4 v165, v[178:181], s[66:67] offset:576
	v_pk_mul_f32 v[64:65], v[178:179], v[196:197]
	v_pk_mul_f32 v[66:67], v[180:181], v[198:199]
	v_cvt_pk_bf16_f32 v64, v64, v65
	v_cvt_pk_bf16_f32 v65, v66, v67
	global_store_dwordx2 v173, v[64:65], s[8:9] offset:288
	v_fmac_f32_e32 v82, v178, v178
	v_fmac_f32_e32 v82, v179, v179
	v_fmac_f32_e32 v82, v180, v180
	v_fmac_f32_e32 v82, v181, v181
	v_add_u32_e32 v165, 0xa0000, v165
	v_lshrrev_b32_e32 v173, 1, v165
	global_load_dwordx4 v[178:181], v164, s[98:99] offset:576
	v_add_u32_e32 v164, 0x20000, v164
	s_waitcnt vmcnt(21)
	v_pk_fma_f32 v[200:201], v[60:61], v[72:73], v[200:201]
	v_pk_fma_f32 v[202:203], v[62:63], v[74:75], v[202:203]
	global_store_dwordx4 v165, v[200:203], s[66:67]
	v_pk_mul_f32 v[60:61], v[200:201], v[182:183]
	v_pk_mul_f32 v[62:63], v[202:203], v[184:185]
	v_cvt_pk_bf16_f32 v60, v60, v61
	v_cvt_pk_bf16_f32 v61, v62, v63
	global_store_dwordx2 v173, v[60:61], s[8:9]
	v_mul_f32_e32 v62, v200, v200
	v_fmac_f32_e32 v62, v201, v201
	v_fmac_f32_e32 v62, v202, v202
	v_fmac_f32_e32 v62, v203, v203
	global_load_dwordx4 v[200:203], v164, s[98:99]
	s_waitcnt vmcnt(21)
	v_pk_fma_f32 v[204:205], v[56:57], v[84:85], v[204:205]
	v_pk_fma_f32 v[206:207], v[58:59], v[86:87], v[206:207]
	global_store_dwordx4 v165, v[204:207], s[66:67] offset:64
	v_pk_mul_f32 v[56:57], v[204:205], v[188:189]
	v_pk_mul_f32 v[58:59], v[206:207], v[190:191]
	v_cvt_pk_bf16_f32 v56, v56, v57
	v_cvt_pk_bf16_f32 v57, v58, v59
	global_store_dwordx2 v173, v[56:57], s[8:9] offset:32
	v_fmac_f32_e32 v62, v204, v204
	v_fmac_f32_e32 v62, v205, v205
	v_fmac_f32_e32 v62, v206, v206
	v_fmac_f32_e32 v62, v207, v207
	global_load_dwordx4 v[204:207], v164, s[98:99] offset:64
	s_waitcnt vmcnt(21)
	v_pk_fma_f32 v[208:209], v[52:53], v[92:93], v[208:209]
	v_pk_fma_f32 v[210:211], v[54:55], v[94:95], v[210:211]
	global_store_dwordx4 v165, v[208:211], s[66:67] offset:512
	v_pk_mul_f32 v[52:53], v[208:209], v[192:193]
	v_pk_mul_f32 v[54:55], v[210:211], v[194:195]
	v_cvt_pk_bf16_f32 v52, v52, v53
	v_cvt_pk_bf16_f32 v53, v54, v55
	global_store_dwordx2 v173, v[52:53], s[8:9] offset:256
	v_fmac_f32_e32 v62, v208, v208
	v_fmac_f32_e32 v62, v209, v209
	v_fmac_f32_e32 v62, v210, v210
	v_fmac_f32_e32 v62, v211, v211
	global_load_dwordx4 v[208:211], v164, s[98:99] offset:512
	s_waitcnt vmcnt(21)
	v_pk_fma_f32 v[212:213], v[48:49], v[96:97], v[212:213]
	v_pk_fma_f32 v[214:215], v[50:51], v[98:99], v[214:215]
	global_store_dwordx4 v165, v[212:215], s[66:67] offset:576
	v_pk_mul_f32 v[48:49], v[212:213], v[196:197]
	v_pk_mul_f32 v[50:51], v[214:215], v[198:199]
	v_cvt_pk_bf16_f32 v48, v48, v49
	v_cvt_pk_bf16_f32 v49, v50, v51
	global_store_dwordx2 v173, v[48:49], s[8:9] offset:288
	v_fmac_f32_e32 v62, v212, v212
	v_fmac_f32_e32 v62, v213, v213
	v_fmac_f32_e32 v62, v214, v214
	v_fmac_f32_e32 v62, v215, v215
	v_add_u32_e32 v165, 0x20000, v165
	v_lshrrev_b32_e32 v173, 1, v165
	global_load_dwordx4 v[212:215], v164, s[98:99] offset:576
	v_add_u32_e32 v164, 0x20000, v164
	s_waitcnt vmcnt(21)
	v_pk_fma_f32 v[156:157], v[44:45], v[72:73], v[156:157]
	v_pk_fma_f32 v[158:159], v[46:47], v[74:75], v[158:159]
	global_store_dwordx4 v165, v[156:159], s[66:67]
	v_pk_mul_f32 v[44:45], v[156:157], v[182:183]
	v_pk_mul_f32 v[46:47], v[158:159], v[184:185]
	v_cvt_pk_bf16_f32 v44, v44, v45
	v_cvt_pk_bf16_f32 v45, v46, v47
	global_store_dwordx2 v173, v[44:45], s[8:9]
	v_mul_f32_e32 v46, v156, v156
	v_fmac_f32_e32 v46, v157, v157
	v_fmac_f32_e32 v46, v158, v158
	v_fmac_f32_e32 v46, v159, v159
	global_load_dwordx4 v[156:159], v164, s[98:99]
	s_waitcnt vmcnt(21)
	v_pk_fma_f32 v[160:161], v[40:41], v[84:85], v[160:161]
	v_pk_fma_f32 v[162:163], v[42:43], v[86:87], v[162:163]
	global_store_dwordx4 v165, v[160:163], s[66:67] offset:64
	v_pk_mul_f32 v[40:41], v[160:161], v[188:189]
	v_pk_mul_f32 v[42:43], v[162:163], v[190:191]
	v_cvt_pk_bf16_f32 v40, v40, v41
	v_cvt_pk_bf16_f32 v41, v42, v43
	global_store_dwordx2 v173, v[40:41], s[8:9] offset:32
	v_fmac_f32_e32 v46, v160, v160
	v_fmac_f32_e32 v46, v161, v161
	v_fmac_f32_e32 v46, v162, v162
	v_fmac_f32_e32 v46, v163, v163
	global_load_dwordx4 v[160:163], v164, s[98:99] offset:64
	s_waitcnt vmcnt(21)
	v_pk_fma_f32 v[174:175], v[36:37], v[92:93], v[174:175]
	v_pk_fma_f32 v[176:177], v[38:39], v[94:95], v[176:177]
	global_store_dwordx4 v165, v[174:177], s[66:67] offset:512
	v_pk_mul_f32 v[36:37], v[174:175], v[192:193]
	v_pk_mul_f32 v[38:39], v[176:177], v[194:195]
	v_cvt_pk_bf16_f32 v36, v36, v37
	v_cvt_pk_bf16_f32 v37, v38, v39
	global_store_dwordx2 v173, v[36:37], s[8:9] offset:256
	v_fmac_f32_e32 v46, v174, v174
	v_fmac_f32_e32 v46, v175, v175
	v_fmac_f32_e32 v46, v176, v176
	v_fmac_f32_e32 v46, v177, v177
	global_load_dwordx4 v[174:177], v164, s[98:99] offset:512
	s_waitcnt vmcnt(21)
; __device__ __forceinline__ unsigned cvt_pk_bf16(float lo, float hi) { unsigned r; asm volatile("v_cvt_pk_bf16_f32 %0, %1, %2" : "=v"(r) : "v"(lo), "v"(hi)); return r; }
;     __device__ __forceinline__ void operator()(const f32x4 (&acc)[2][2][4][2], const Unit& u, int wr, int wc, int fr, int fq) const {
;     ...
;             for (int m = 0; m < 4; ++m) { const int row = row0 + ai * HALF + m * 16; const size_t off = (size_t)row * 2048 + col0; float ss = 0.f;
; #pragma unroll
;                 for (int bj = 0; bj < 2; ++bj)
; #pragma unroll
;                     for (int n = 0; n < 2; ++n) { const f32x4 bs = __builtin_nontemporal_load((const f32x4*)(base + off + bj * HALF + n * 16)); const f32x4 x1 = bs + gv[bj][n] * acc[ai][bj][m][n];
;                         *(f32x4*)(out + off + bj * HALF + n * 16) = x1; ss += (x1.x * x1.x + x1.y * x1.y) + (x1.z * x1.z + x1.w * x1.w);
;                         const f32x4 hh = x1 * Gv[bj][n]; u32x2 w; w.x = cvt_pk_bf16(hh.x, hh.y); w.y = cvt_pk_bf16(hh.z, hh.w); *(u32x2*)(A2 + off + bj * HALF + n * 16) = w; }
;                 ss += __shfl_xor(ss, 16); ss += __shfl_xor(ss, 32);
;                 if (fq == 0) prow[row] = ss; }
	v_pk_fma_f32 v[178:179], v[32:33], v[96:97], v[178:179]
	v_pk_fma_f32 v[180:181], v[34:35], v[98:99], v[180:181]
	global_store_dwordx4 v165, v[178:181], s[66:67] offset:576
	v_pk_mul_f32 v[32:33], v[178:179], v[196:197]
	v_pk_mul_f32 v[34:35], v[180:181], v[198:199]
	v_cvt_pk_bf16_f32 v32, v32, v33
	v_cvt_pk_bf16_f32 v33, v34, v35
	global_store_dwordx2 v173, v[32:33], s[8:9] offset:288
	v_fmac_f32_e32 v46, v178, v178
	v_fmac_f32_e32 v46, v179, v179
	v_fmac_f32_e32 v46, v180, v180
	v_fmac_f32_e32 v46, v181, v181
	v_add_u32_e32 v165, 0x20000, v165
	v_lshrrev_b32_e32 v173, 1, v165
	global_load_dwordx4 v[178:181], v164, s[98:99] offset:576
	s_waitcnt vmcnt(21)
	v_pk_fma_f32 v[200:201], v[28:29], v[72:73], v[200:201]
	v_pk_fma_f32 v[202:203], v[30:31], v[74:75], v[202:203]
	global_store_dwordx4 v165, v[200:203], s[66:67]
	v_pk_mul_f32 v[28:29], v[200:201], v[182:183]
	v_pk_mul_f32 v[30:31], v[202:203], v[184:185]
	v_cvt_pk_bf16_f32 v28, v28, v29
	v_cvt_pk_bf16_f32 v29, v30, v31
	global_store_dwordx2 v173, v[28:29], s[8:9]
	v_mul_f32_e32 v30, v200, v200
	v_fmac_f32_e32 v30, v201, v201
	v_fmac_f32_e32 v30, v202, v202
	v_fmac_f32_e32 v30, v203, v203
	s_waitcnt vmcnt(20)
	v_pk_fma_f32 v[204:205], v[24:25], v[84:85], v[204:205]
	v_pk_fma_f32 v[206:207], v[26:27], v[86:87], v[206:207]
	global_store_dwordx4 v165, v[204:207], s[66:67] offset:64
	v_pk_mul_f32 v[24:25], v[204:205], v[188:189]
	v_pk_mul_f32 v[26:27], v[206:207], v[190:191]
	v_cvt_pk_bf16_f32 v24, v24, v25
	v_cvt_pk_bf16_f32 v25, v26, v27
	global_store_dwordx2 v173, v[24:25], s[8:9] offset:32
	v_fmac_f32_e32 v30, v204, v204
	v_fmac_f32_e32 v30, v205, v205
	v_fmac_f32_e32 v30, v206, v206
	v_fmac_f32_e32 v30, v207, v207
	s_waitcnt vmcnt(19)
	v_pk_fma_f32 v[208:209], v[20:21], v[92:93], v[208:209]
	v_pk_fma_f32 v[210:211], v[22:23], v[94:95], v[210:211]
	global_store_dwordx4 v165, v[208:211], s[66:67] offset:512
	v_pk_mul_f32 v[20:21], v[208:209], v[192:193]
	v_pk_mul_f32 v[22:23], v[210:211], v[194:195]
	v_cvt_pk_bf16_f32 v20, v20, v21
	v_cvt_pk_bf16_f32 v21, v22, v23
	global_store_dwordx2 v173, v[20:21], s[8:9] offset:256
	v_fmac_f32_e32 v30, v208, v208
	v_fmac_f32_e32 v30, v209, v209
	v_fmac_f32_e32 v30, v210, v210
	v_fmac_f32_e32 v30, v211, v211
	s_waitcnt vmcnt(18)
	v_pk_fma_f32 v[212:213], v[16:17], v[96:97], v[212:213]
	v_pk_fma_f32 v[214:215], v[18:19], v[98:99], v[214:215]
	global_store_dwordx4 v165, v[212:215], s[66:67] offset:576
	v_pk_mul_f32 v[16:17], v[212:213], v[196:197]
	v_pk_mul_f32 v[18:19], v[214:215], v[198:199]
	v_cvt_pk_bf16_f32 v16, v16, v17
	v_cvt_pk_bf16_f32 v17, v18, v19
	global_store_dwordx2 v173, v[16:17], s[8:9] offset:288
	v_fmac_f32_e32 v30, v212, v212
	v_fmac_f32_e32 v30, v213, v213
	v_fmac_f32_e32 v30, v214, v214
	v_fmac_f32_e32 v30, v215, v215
	v_add_u32_e32 v165, 0x20000, v165
	v_lshrrev_b32_e32 v173, 1, v165
	s_waitcnt vmcnt(17)
	v_pk_fma_f32 v[156:157], v[12:13], v[72:73], v[156:157]
	v_pk_fma_f32 v[158:159], v[14:15], v[74:75], v[158:159]
	global_store_dwordx4 v165, v[156:159], s[66:67]
	v_pk_mul_f32 v[12:13], v[156:157], v[182:183]
	v_pk_mul_f32 v[14:15], v[158:159], v[184:185]
	v_cvt_pk_bf16_f32 v12, v12, v13
	v_cvt_pk_bf16_f32 v13, v14, v15
	global_store_dwordx2 v173, v[12:13], s[8:9]
	v_mul_f32_e32 v14, v156, v156
	v_fmac_f32_e32 v14, v157, v157
	v_fmac_f32_e32 v14, v158, v158
	v_fmac_f32_e32 v14, v159, v159
	s_waitcnt vmcnt(16)
	v_pk_fma_f32 v[160:161], v[8:9], v[84:85], v[160:161]
	v_pk_fma_f32 v[162:163], v[10:11], v[86:87], v[162:163]
	global_store_dwordx4 v165, v[160:163], s[66:67] offset:64
	v_pk_mul_f32 v[8:9], v[160:161], v[188:189]
	v_pk_mul_f32 v[10:11], v[162:163], v[190:191]
	v_cvt_pk_bf16_f32 v8, v8, v9
	v_cvt_pk_bf16_f32 v9, v10, v11
	global_store_dwordx2 v173, v[8:9], s[8:9] offset:32
	v_fmac_f32_e32 v14, v160, v160
	v_fmac_f32_e32 v14, v161, v161
	v_fmac_f32_e32 v14, v162, v162
	v_fmac_f32_e32 v14, v163, v163
	s_waitcnt vmcnt(15)
	v_pk_fma_f32 v[174:175], v[4:5], v[92:93], v[174:175]
	v_pk_fma_f32 v[176:177], v[6:7], v[94:95], v[176:177]
	global_store_dwordx4 v165, v[174:177], s[66:67] offset:512
	v_pk_mul_f32 v[4:5], v[174:175], v[192:193]
	v_pk_mul_f32 v[6:7], v[176:177], v[194:195]
	v_cvt_pk_bf16_f32 v4, v4, v5
	v_cvt_pk_bf16_f32 v5, v6, v7
	global_store_dwordx2 v173, v[4:5], s[8:9] offset:256
	v_fmac_f32_e32 v14, v174, v174
	v_fmac_f32_e32 v14, v175, v175
	v_fmac_f32_e32 v14, v176, v176
	v_fmac_f32_e32 v14, v177, v177
	s_waitcnt vmcnt(14)
	v_pk_fma_f32 v[178:179], v[0:1], v[96:97], v[178:179]
	v_pk_fma_f32 v[180:181], v[2:3], v[98:99], v[180:181]
	global_store_dwordx4 v165, v[178:181], s[66:67] offset:576
	v_pk_mul_f32 v[0:1], v[178:179], v[196:197]
	v_pk_mul_f32 v[2:3], v[180:181], v[198:199]
	v_cvt_pk_bf16_f32 v0, v0, v1
	v_cvt_pk_bf16_f32 v1, v2, v3
	global_store_dwordx2 v173, v[0:1], s[8:9] offset:288
	v_fmac_f32_e32 v14, v178, v178
	v_fmac_f32_e32 v14, v179, v179
	v_fmac_f32_e32 v14, v180, v180
	v_fmac_f32_e32 v14, v181, v181
	ds_bpermute_b32 v143, v216, v142
	ds_bpermute_b32 v127, v216, v126
	ds_bpermute_b32 v111, v216, v110
	ds_bpermute_b32 v83, v216, v82
	ds_bpermute_b32 v63, v216, v62
	ds_bpermute_b32 v47, v216, v46
	ds_bpermute_b32 v31, v216, v30
	ds_bpermute_b32 v15, v216, v14
	s_waitcnt lgkmcnt(0)
	v_add_f32_e32 v142, v142, v143
	v_add_f32_e32 v126, v126, v127
	v_add_f32_e32 v110, v110, v111
	v_add_f32_e32 v82, v82, v83
	v_add_f32_e32 v62, v62, v63
	v_add_f32_e32 v46, v46, v47
	v_add_f32_e32 v30, v30, v31
	v_add_f32_e32 v14, v14, v15
	ds_bpermute_b32 v143, v217, v142
	ds_bpermute_b32 v127, v217, v126
	ds_bpermute_b32 v111, v217, v110
	ds_bpermute_b32 v83, v217, v82
	ds_bpermute_b32 v63, v217, v62
	ds_bpermute_b32 v47, v217, v46
	ds_bpermute_b32 v31, v217, v30
	ds_bpermute_b32 v15, v217, v14
	s_lshl_b32 s25, s34, 2
	s_or_b32 s25, s25, s47
	s_lshl_b32 s25, s25, 16
	v_lshl_add_u32 v164, s36, 8, v166
	v_lshl_add_u32 v164, v164, 2, s25
	s_waitcnt lgkmcnt(0)
	v_add_f32_e32 v142, v142, v143
	v_add_f32_e32 v126, v126, v127
	v_add_f32_e32 v110, v110, v111
	v_add_f32_e32 v82, v82, v83
	v_add_f32_e32 v62, v62, v63
	v_add_f32_e32 v46, v46, v47
	v_add_f32_e32 v30, v30, v31
	v_add_f32_e32 v14, v14, v15
	s_and_saveexec_b64 s[100:101], s[4:5]
	global_store_dword v164, v142, s[48:49]
	global_store_dword v164, v126, s[48:49] offset:64
	global_store_dword v164, v110, s[48:49] offset:128
	global_store_dword v164, v82, s[48:49] offset:192
	global_store_dword v164, v62, s[48:49] offset:512
	global_store_dword v164, v46, s[48:49] offset:576
	global_store_dword v164, v30, s[48:49] offset:640
	global_store_dword v164, v14, s[48:49] offset:704
	s_or_b64 exec, exec, s[100:101]
	s_andn2_b64 vcc, exec, s[6:7]
	s_mov_b64 s[6:7], -1
	s_cbranch_vccnz .LBB0_886
	s_andn2_b64 vcc, exec, s[10:11]
	s_cbranch_vccnz .LBB0_885
	s_barrier
	s_branch .LBB0_885
